# attention mode-1/3 softmax+PV tile bodies (6 blocks in MoBA/swa/nsa_win): packed f32 scale (v_pk_fma_f32) and packed partial sums, interleaved with v_exp, in-place bf16 pack
# baseline (speedup 1.0000x reference)
.LBB0_510:
	v_cmp_neq_f32_e32 vcc, s85, v119
	s_nop 1
	v_cndmask_b32_e64 v120, 0, -v119, vcc
	v_cndmask_b32_e64 v120, v220, v120, s[74:75]
	v_mov_b32_e32 v130, 0x3e38aa3b
	v_lshlrev_b32_e32 v131, 1, v112
	v_add3_u32 v121, s16, v105, v131
	v_add3_u32 v131, s16, v113, v131
	s_setprio 1
	ds_read_b128 v[122:125], v121 offset:9216
	v_pk_fma_f32 v[50:51], v[50:51], v[130:131], v[120:121] op_sel_hi:[1,0,0]
	v_pk_fma_f32 v[52:53], v[52:53], v[130:131], v[120:121] op_sel_hi:[1,0,0]
	v_exp_f32_e32 v50, v50
	v_exp_f32_e32 v51, v51
	v_exp_f32_e32 v52, v52
	v_pk_fma_f32 v[54:55], v[54:55], v[130:131], v[120:121] op_sel_hi:[1,0,0]
	v_exp_f32_e32 v53, v53
	v_exp_f32_e32 v54, v54
	v_pk_fma_f32 v[56:57], v[56:57], v[130:131], v[120:121] op_sel_hi:[1,0,0]
	v_exp_f32_e32 v55, v55
	v_exp_f32_e32 v56, v56
	v_exp_f32_e32 v57, v57
	v_pk_fma_f32 v[58:59], v[58:59], v[130:131], v[120:121] op_sel_hi:[1,0,0]
	v_pk_fma_f32 v[60:61], v[60:61], v[130:131], v[120:121] op_sel_hi:[1,0,0]
	v_exp_f32_e32 v58, v58
	v_pk_add_f32 v[126:127], v[50:51], v[52:53]
	v_exp_f32_e32 v59, v59
	v_pk_add_f32 v[126:127], v[126:127], v[54:55]
	v_exp_f32_e32 v60, v60
	v_pk_fma_f32 v[62:63], v[62:63], v[130:131], v[120:121] op_sel_hi:[1,0,0]
	v_exp_f32_e32 v61, v61
	v_pk_add_f32 v[126:127], v[126:127], v[56:57]
	v_exp_f32_e32 v62, v62
	v_pk_fma_f32 v[64:65], v[64:65], v[130:131], v[120:121] op_sel_hi:[1,0,0]
	v_exp_f32_e32 v63, v63
	v_cvt_pk_bf16_f32 v50, v50, v51
	v_exp_f32_e32 v64, v64
	v_cvt_pk_bf16_f32 v51, v52, v53
	v_exp_f32_e32 v65, v65
	v_cvt_pk_bf16_f32 v52, v54, v55
	v_cvt_pk_bf16_f32 v53, v56, v57
	v_pk_add_f32 v[56:57], v[126:127], v[58:59]
	ds_read_b128 v[126:129], v131 offset:9216
	s_waitcnt lgkmcnt(1)
	v_mfma_f32_32x32x16_bf16 v[18:33], v[122:125], v[50:53], v[18:33]
	ds_read_b128 v[122:125], v121 offset:9248
	s_waitcnt lgkmcnt(1)
	v_mfma_f32_32x32x16_bf16 v[2:17], v[126:129], v[50:53], v[2:17]
	ds_read_b128 v[126:129], v131 offset:9248
	v_pk_fma_f32 v[34:35], v[34:35], v[130:131], v[120:121] op_sel_hi:[1,0,0]
	v_pk_fma_f32 v[36:37], v[36:37], v[130:131], v[120:121] op_sel_hi:[1,0,0]
	v_exp_f32_e32 v34, v34
	v_pk_add_f32 v[56:57], v[56:57], v[60:61]
	v_exp_f32_e32 v35, v35
	v_pk_add_f32 v[56:57], v[56:57], v[62:63]
	v_exp_f32_e32 v36, v36
	v_pk_fma_f32 v[38:39], v[38:39], v[130:131], v[120:121] op_sel_hi:[1,0,0]
	v_exp_f32_e32 v37, v37
	v_pk_add_f32 v[56:57], v[56:57], v[64:65]
	v_exp_f32_e32 v38, v38
	v_pk_fma_f32 v[40:41], v[40:41], v[130:131], v[120:121] op_sel_hi:[1,0,0]
	v_exp_f32_e32 v39, v39
	v_cvt_pk_bf16_f32 v58, v58, v59
	v_exp_f32_e32 v40, v40
	v_cvt_pk_bf16_f32 v59, v60, v61
	v_exp_f32_e32 v41, v41
	v_cvt_pk_bf16_f32 v60, v62, v63
	v_cvt_pk_bf16_f32 v61, v64, v65
	s_waitcnt lgkmcnt(1)
	s_nop 0
	v_mfma_f32_32x32x16_bf16 v[18:33], v[122:125], v[58:61], v[18:33]
	ds_read_b128 v[122:125], v121 offset:9280
	s_waitcnt lgkmcnt(1)
	v_mfma_f32_32x32x16_bf16 v[2:17], v[126:129], v[58:61], v[2:17]
	ds_read_b128 v[126:129], v131 offset:9280
	v_pk_fma_f32 v[42:43], v[42:43], v[130:131], v[120:121] op_sel_hi:[1,0,0]
	v_pk_fma_f32 v[44:45], v[44:45], v[130:131], v[120:121] op_sel_hi:[1,0,0]
	v_exp_f32_e32 v42, v42
	v_pk_add_f32 v[56:57], v[56:57], v[34:35]
	v_exp_f32_e32 v43, v43
	v_pk_add_f32 v[56:57], v[56:57], v[36:37]
	v_exp_f32_e32 v44, v44
	v_pk_fma_f32 v[46:47], v[46:47], v[130:131], v[120:121] op_sel_hi:[1,0,0]
	v_exp_f32_e32 v45, v45
	v_pk_add_f32 v[56:57], v[56:57], v[38:39]
	v_exp_f32_e32 v46, v46
	v_pk_fma_f32 v[48:49], v[48:49], v[130:131], v[120:121] op_sel_hi:[1,0,0]
	v_exp_f32_e32 v47, v47
	v_pk_add_f32 v[56:57], v[56:57], v[40:41]
	v_exp_f32_e32 v48, v48
	v_cvt_pk_bf16_f32 v34, v34, v35
	v_exp_f32_e32 v49, v49
	v_cvt_pk_bf16_f32 v35, v36, v37
	v_cvt_pk_bf16_f32 v36, v38, v39
	v_cvt_pk_bf16_f32 v37, v40, v41
	s_waitcnt lgkmcnt(1)
	s_nop 0
	v_mfma_f32_32x32x16_bf16 v[18:33], v[122:125], v[34:37], v[18:33]
	ds_read_b128 v[122:125], v121 offset:9312
	s_waitcnt lgkmcnt(1)
	v_mfma_f32_32x32x16_bf16 v[2:17], v[126:129], v[34:37], v[2:17]
	ds_read_b128 v[126:129], v131 offset:9312
	v_pk_add_f32 v[56:57], v[56:57], v[42:43]
	v_pk_add_f32 v[56:57], v[56:57], v[44:45]
	v_pk_add_f32 v[56:57], v[56:57], v[46:47]
	v_pk_add_f32 v[56:57], v[56:57], v[48:49]
	v_cvt_pk_bf16_f32 v42, v42, v43
	v_cvt_pk_bf16_f32 v43, v44, v45
	v_cvt_pk_bf16_f32 v44, v46, v47
	v_cvt_pk_bf16_f32 v45, v48, v49
	v_add_f32_e32 v56, v56, v57
	s_waitcnt lgkmcnt(1)
	v_mfma_f32_32x32x16_bf16 v[18:33], v[122:125], v[42:45], v[18:33]
	v_add_f32_e32 v117, v117, v56
	s_waitcnt lgkmcnt(0)
	v_mfma_f32_32x32x16_bf16 v[2:17], v[126:129], v[42:45], v[2:17]

.LBB0_520:
	v_cmp_neq_f32_e32 vcc, s85, v119
	s_nop 1
	v_cndmask_b32_e64 v120, 0, -v119, vcc
	v_mov_b32_e32 v130, 0x3e38aa3b
	v_lshlrev_b32_e32 v131, 1, v112
	v_add3_u32 v121, s16, v105, v131
	v_add3_u32 v131, s16, v113, v131
	s_setprio 1
	ds_read_b128 v[122:125], v121 offset:9216
	v_pk_fma_f32 v[50:51], v[50:51], v[130:131], v[120:121] op_sel_hi:[1,0,0]
	v_pk_fma_f32 v[52:53], v[52:53], v[130:131], v[120:121] op_sel_hi:[1,0,0]
	v_exp_f32_e32 v50, v50
	v_exp_f32_e32 v51, v51
	v_exp_f32_e32 v52, v52
	v_pk_fma_f32 v[54:55], v[54:55], v[130:131], v[120:121] op_sel_hi:[1,0,0]
	v_exp_f32_e32 v53, v53
	v_exp_f32_e32 v54, v54
	v_pk_fma_f32 v[56:57], v[56:57], v[130:131], v[120:121] op_sel_hi:[1,0,0]
	v_exp_f32_e32 v55, v55
	v_exp_f32_e32 v56, v56
	v_exp_f32_e32 v57, v57
	v_pk_fma_f32 v[58:59], v[58:59], v[130:131], v[120:121] op_sel_hi:[1,0,0]
	v_pk_fma_f32 v[60:61], v[60:61], v[130:131], v[120:121] op_sel_hi:[1,0,0]
	v_exp_f32_e32 v58, v58
	v_pk_add_f32 v[126:127], v[50:51], v[52:53]
	v_exp_f32_e32 v59, v59
	v_pk_add_f32 v[126:127], v[126:127], v[54:55]
	v_exp_f32_e32 v60, v60
	v_pk_fma_f32 v[62:63], v[62:63], v[130:131], v[120:121] op_sel_hi:[1,0,0]
	v_exp_f32_e32 v61, v61
	v_pk_add_f32 v[126:127], v[126:127], v[56:57]
	v_exp_f32_e32 v62, v62
	v_pk_fma_f32 v[64:65], v[64:65], v[130:131], v[120:121] op_sel_hi:[1,0,0]
	v_exp_f32_e32 v63, v63
	v_cvt_pk_bf16_f32 v50, v50, v51
	v_exp_f32_e32 v64, v64
	v_cvt_pk_bf16_f32 v51, v52, v53
	v_exp_f32_e32 v65, v65
	v_cvt_pk_bf16_f32 v52, v54, v55
	v_cvt_pk_bf16_f32 v53, v56, v57
	v_pk_add_f32 v[56:57], v[126:127], v[58:59]
	ds_read_b128 v[126:129], v131 offset:9216
	s_waitcnt lgkmcnt(1)
	v_mfma_f32_32x32x16_bf16 v[18:33], v[122:125], v[50:53], v[18:33]
	ds_read_b128 v[122:125], v121 offset:9248
	s_waitcnt lgkmcnt(1)
	v_mfma_f32_32x32x16_bf16 v[2:17], v[126:129], v[50:53], v[2:17]
	ds_read_b128 v[126:129], v131 offset:9248
	v_pk_fma_f32 v[34:35], v[34:35], v[130:131], v[120:121] op_sel_hi:[1,0,0]
	v_pk_fma_f32 v[36:37], v[36:37], v[130:131], v[120:121] op_sel_hi:[1,0,0]
	v_exp_f32_e32 v34, v34
	v_pk_add_f32 v[56:57], v[56:57], v[60:61]
	v_exp_f32_e32 v35, v35
	v_pk_add_f32 v[56:57], v[56:57], v[62:63]
	v_exp_f32_e32 v36, v36
	v_pk_fma_f32 v[38:39], v[38:39], v[130:131], v[120:121] op_sel_hi:[1,0,0]
	v_exp_f32_e32 v37, v37
	v_pk_add_f32 v[56:57], v[56:57], v[64:65]
	v_exp_f32_e32 v38, v38
	v_pk_fma_f32 v[40:41], v[40:41], v[130:131], v[120:121] op_sel_hi:[1,0,0]
	v_exp_f32_e32 v39, v39
	v_cvt_pk_bf16_f32 v58, v58, v59
	v_exp_f32_e32 v40, v40
	v_cvt_pk_bf16_f32 v59, v60, v61
	v_exp_f32_e32 v41, v41
	v_cvt_pk_bf16_f32 v60, v62, v63
	v_cvt_pk_bf16_f32 v61, v64, v65
	s_waitcnt lgkmcnt(1)
	s_nop 0
	v_mfma_f32_32x32x16_bf16 v[18:33], v[122:125], v[58:61], v[18:33]
	ds_read_b128 v[122:125], v121 offset:9280
	s_waitcnt lgkmcnt(1)
	v_mfma_f32_32x32x16_bf16 v[2:17], v[126:129], v[58:61], v[2:17]
	ds_read_b128 v[126:129], v131 offset:9280
	v_pk_fma_f32 v[42:43], v[42:43], v[130:131], v[120:121] op_sel_hi:[1,0,0]
	v_pk_fma_f32 v[44:45], v[44:45], v[130:131], v[120:121] op_sel_hi:[1,0,0]
	v_exp_f32_e32 v42, v42
	v_pk_add_f32 v[56:57], v[56:57], v[34:35]
	v_exp_f32_e32 v43, v43
	v_pk_add_f32 v[56:57], v[56:57], v[36:37]
	v_exp_f32_e32 v44, v44
	v_pk_fma_f32 v[46:47], v[46:47], v[130:131], v[120:121] op_sel_hi:[1,0,0]
	v_exp_f32_e32 v45, v45
	v_pk_add_f32 v[56:57], v[56:57], v[38:39]
	v_exp_f32_e32 v46, v46
	v_pk_fma_f32 v[48:49], v[48:49], v[130:131], v[120:121] op_sel_hi:[1,0,0]
	v_exp_f32_e32 v47, v47
	v_pk_add_f32 v[56:57], v[56:57], v[40:41]
	v_exp_f32_e32 v48, v48
	v_cvt_pk_bf16_f32 v34, v34, v35
	v_exp_f32_e32 v49, v49
	v_cvt_pk_bf16_f32 v35, v36, v37
	v_cvt_pk_bf16_f32 v36, v38, v39
	v_cvt_pk_bf16_f32 v37, v40, v41
	s_waitcnt lgkmcnt(1)
	s_nop 0
	v_mfma_f32_32x32x16_bf16 v[18:33], v[122:125], v[34:37], v[18:33]
	ds_read_b128 v[122:125], v121 offset:9312
	s_waitcnt lgkmcnt(1)
	v_mfma_f32_32x32x16_bf16 v[2:17], v[126:129], v[34:37], v[2:17]
	ds_read_b128 v[126:129], v131 offset:9312
	v_pk_add_f32 v[56:57], v[56:57], v[42:43]
	v_pk_add_f32 v[56:57], v[56:57], v[44:45]
	v_pk_add_f32 v[56:57], v[56:57], v[46:47]
	v_pk_add_f32 v[56:57], v[56:57], v[48:49]
	v_cvt_pk_bf16_f32 v42, v42, v43
	v_cvt_pk_bf16_f32 v43, v44, v45
	v_cvt_pk_bf16_f32 v44, v46, v47
	v_cvt_pk_bf16_f32 v45, v48, v49
	v_add_f32_e32 v56, v56, v57
	s_waitcnt lgkmcnt(1)
	v_mfma_f32_32x32x16_bf16 v[18:33], v[122:125], v[42:45], v[18:33]
	v_add_f32_e32 v117, v117, v56
	s_waitcnt lgkmcnt(0)
	v_mfma_f32_32x32x16_bf16 v[2:17], v[126:129], v[42:45], v[2:17]

.LBB0_612:
	v_cmp_neq_f32_e32 vcc, s85, v152
	s_nop 1
	v_cndmask_b32_e64 v66, 0, -v152, vcc
	v_mov_b32_e32 v76, 0x3e38aa3b
	v_lshlrev_b32_e32 v77, 1, v147
	v_add3_u32 v67, s37, v146, v77
	v_add3_u32 v77, s37, v148, v77
	s_setprio 1
	ds_read_b128 v[68:71], v67 offset:9216
	v_pk_fma_f32 v[50:51], v[50:51], v[76:77], v[66:67] op_sel_hi:[1,0,0]
	v_pk_fma_f32 v[52:53], v[52:53], v[76:77], v[66:67] op_sel_hi:[1,0,0]
	v_exp_f32_e32 v50, v50
	v_exp_f32_e32 v51, v51
	v_exp_f32_e32 v52, v52
	v_pk_fma_f32 v[54:55], v[54:55], v[76:77], v[66:67] op_sel_hi:[1,0,0]
	v_exp_f32_e32 v53, v53
	v_exp_f32_e32 v54, v54
	v_pk_fma_f32 v[56:57], v[56:57], v[76:77], v[66:67] op_sel_hi:[1,0,0]
	v_exp_f32_e32 v55, v55
	v_exp_f32_e32 v56, v56
	v_exp_f32_e32 v57, v57
	v_pk_fma_f32 v[58:59], v[58:59], v[76:77], v[66:67] op_sel_hi:[1,0,0]
	v_pk_fma_f32 v[60:61], v[60:61], v[76:77], v[66:67] op_sel_hi:[1,0,0]
	v_exp_f32_e32 v58, v58
	v_pk_add_f32 v[72:73], v[50:51], v[52:53]
	v_exp_f32_e32 v59, v59
	v_pk_add_f32 v[72:73], v[72:73], v[54:55]
	v_exp_f32_e32 v60, v60
	v_pk_fma_f32 v[62:63], v[62:63], v[76:77], v[66:67] op_sel_hi:[1,0,0]
	v_exp_f32_e32 v61, v61
	v_pk_add_f32 v[72:73], v[72:73], v[56:57]
	v_exp_f32_e32 v62, v62
	v_pk_fma_f32 v[64:65], v[64:65], v[76:77], v[66:67] op_sel_hi:[1,0,0]
	v_exp_f32_e32 v63, v63
	v_cvt_pk_bf16_f32 v50, v50, v51
	v_exp_f32_e32 v64, v64
	v_cvt_pk_bf16_f32 v51, v52, v53
	v_exp_f32_e32 v65, v65
	v_cvt_pk_bf16_f32 v52, v54, v55
	v_cvt_pk_bf16_f32 v53, v56, v57
	v_pk_add_f32 v[56:57], v[72:73], v[58:59]
	ds_read_b128 v[72:75], v77 offset:9216
	s_waitcnt lgkmcnt(1)
	v_mfma_f32_32x32x16_bf16 v[2:17], v[68:71], v[50:53], v[2:17]
	ds_read_b128 v[68:71], v67 offset:9248
	s_waitcnt lgkmcnt(1)
	v_mfma_f32_32x32x16_bf16 v[18:33], v[72:75], v[50:53], v[18:33]
	ds_read_b128 v[72:75], v77 offset:9248
	v_pk_fma_f32 v[34:35], v[34:35], v[76:77], v[66:67] op_sel_hi:[1,0,0]
	v_pk_fma_f32 v[36:37], v[36:37], v[76:77], v[66:67] op_sel_hi:[1,0,0]
	v_exp_f32_e32 v34, v34
	v_pk_add_f32 v[56:57], v[56:57], v[60:61]
	v_exp_f32_e32 v35, v35
	v_pk_add_f32 v[56:57], v[56:57], v[62:63]
	v_exp_f32_e32 v36, v36
	v_pk_fma_f32 v[38:39], v[38:39], v[76:77], v[66:67] op_sel_hi:[1,0,0]
	v_exp_f32_e32 v37, v37
	v_pk_add_f32 v[56:57], v[56:57], v[64:65]
	v_exp_f32_e32 v38, v38
	v_pk_fma_f32 v[40:41], v[40:41], v[76:77], v[66:67] op_sel_hi:[1,0,0]
	v_exp_f32_e32 v39, v39
	v_cvt_pk_bf16_f32 v58, v58, v59
	v_exp_f32_e32 v40, v40
	v_cvt_pk_bf16_f32 v59, v60, v61
	v_exp_f32_e32 v41, v41
	v_cvt_pk_bf16_f32 v60, v62, v63
	v_cvt_pk_bf16_f32 v61, v64, v65
	s_waitcnt lgkmcnt(1)
	s_nop 0
	v_mfma_f32_32x32x16_bf16 v[2:17], v[68:71], v[58:61], v[2:17]
	ds_read_b128 v[68:71], v67 offset:9280
	s_waitcnt lgkmcnt(1)
	v_mfma_f32_32x32x16_bf16 v[18:33], v[72:75], v[58:61], v[18:33]
	ds_read_b128 v[72:75], v77 offset:9280
	v_pk_fma_f32 v[42:43], v[42:43], v[76:77], v[66:67] op_sel_hi:[1,0,0]
	v_pk_fma_f32 v[44:45], v[44:45], v[76:77], v[66:67] op_sel_hi:[1,0,0]
	v_exp_f32_e32 v42, v42
	v_pk_add_f32 v[56:57], v[56:57], v[34:35]
	v_exp_f32_e32 v43, v43
	v_pk_add_f32 v[56:57], v[56:57], v[36:37]
	v_exp_f32_e32 v44, v44
	v_pk_fma_f32 v[46:47], v[46:47], v[76:77], v[66:67] op_sel_hi:[1,0,0]
	v_exp_f32_e32 v45, v45
	v_pk_add_f32 v[56:57], v[56:57], v[38:39]
	v_exp_f32_e32 v46, v46
	v_pk_fma_f32 v[48:49], v[48:49], v[76:77], v[66:67] op_sel_hi:[1,0,0]
	v_exp_f32_e32 v47, v47
	v_pk_add_f32 v[56:57], v[56:57], v[40:41]
	v_exp_f32_e32 v48, v48
	v_cvt_pk_bf16_f32 v34, v34, v35
	v_exp_f32_e32 v49, v49
	v_cvt_pk_bf16_f32 v35, v36, v37
	v_cvt_pk_bf16_f32 v36, v38, v39
	v_cvt_pk_bf16_f32 v37, v40, v41
	s_waitcnt lgkmcnt(1)
	s_nop 0
	v_mfma_f32_32x32x16_bf16 v[2:17], v[68:71], v[34:37], v[2:17]
	ds_read_b128 v[68:71], v67 offset:9312
	s_waitcnt lgkmcnt(1)
	v_mfma_f32_32x32x16_bf16 v[18:33], v[72:75], v[34:37], v[18:33]
	ds_read_b128 v[72:75], v77 offset:9312
	v_pk_add_f32 v[56:57], v[56:57], v[42:43]
	v_pk_add_f32 v[56:57], v[56:57], v[44:45]
	v_pk_add_f32 v[56:57], v[56:57], v[46:47]
	v_pk_add_f32 v[56:57], v[56:57], v[48:49]
	v_cvt_pk_bf16_f32 v42, v42, v43
	v_cvt_pk_bf16_f32 v43, v44, v45
	v_cvt_pk_bf16_f32 v44, v46, v47
	v_cvt_pk_bf16_f32 v45, v48, v49
	v_add_f32_e32 v56, v56, v57
	s_waitcnt lgkmcnt(1)
	v_mfma_f32_32x32x16_bf16 v[2:17], v[68:71], v[42:45], v[2:17]
	v_add_f32_e32 v133, v133, v56
	s_waitcnt lgkmcnt(0)
	v_mfma_f32_32x32x16_bf16 v[18:33], v[72:75], v[42:45], v[18:33]

.LBB0_766:
	v_cmp_neq_f32_e32 vcc, s85, v152
	s_nop 1
	v_cndmask_b32_e64 v66, 0, -v152, vcc
	v_mov_b32_e32 v76, 0x3e38aa3b
	v_lshlrev_b32_e32 v77, 1, v146
	v_add3_u32 v67, s76, v139, v77
	v_add3_u32 v77, s76, v147, v77
	s_setprio 1
	ds_read_b128 v[68:71], v67 offset:9216
	v_pk_fma_f32 v[50:51], v[50:51], v[76:77], v[66:67] op_sel_hi:[1,0,0]
	v_pk_fma_f32 v[52:53], v[52:53], v[76:77], v[66:67] op_sel_hi:[1,0,0]
	v_exp_f32_e32 v50, v50
	v_exp_f32_e32 v51, v51
	v_exp_f32_e32 v52, v52
	v_pk_fma_f32 v[54:55], v[54:55], v[76:77], v[66:67] op_sel_hi:[1,0,0]
	v_exp_f32_e32 v53, v53
	v_exp_f32_e32 v54, v54
	v_pk_fma_f32 v[56:57], v[56:57], v[76:77], v[66:67] op_sel_hi:[1,0,0]
	v_exp_f32_e32 v55, v55
	v_exp_f32_e32 v56, v56
	v_exp_f32_e32 v57, v57
	v_pk_fma_f32 v[58:59], v[58:59], v[76:77], v[66:67] op_sel_hi:[1,0,0]
	v_pk_fma_f32 v[60:61], v[60:61], v[76:77], v[66:67] op_sel_hi:[1,0,0]
	v_exp_f32_e32 v58, v58
	v_pk_add_f32 v[72:73], v[50:51], v[52:53]
	v_exp_f32_e32 v59, v59
	v_pk_add_f32 v[72:73], v[72:73], v[54:55]
	v_exp_f32_e32 v60, v60
	v_pk_fma_f32 v[62:63], v[62:63], v[76:77], v[66:67] op_sel_hi:[1,0,0]
	v_exp_f32_e32 v61, v61
	v_pk_add_f32 v[72:73], v[72:73], v[56:57]
	v_exp_f32_e32 v62, v62
	v_pk_fma_f32 v[64:65], v[64:65], v[76:77], v[66:67] op_sel_hi:[1,0,0]
	v_exp_f32_e32 v63, v63
	v_cvt_pk_bf16_f32 v50, v50, v51
	v_exp_f32_e32 v64, v64
	v_cvt_pk_bf16_f32 v51, v52, v53
	v_exp_f32_e32 v65, v65
	v_cvt_pk_bf16_f32 v52, v54, v55
	v_cvt_pk_bf16_f32 v53, v56, v57
	v_pk_add_f32 v[56:57], v[72:73], v[58:59]
	ds_read_b128 v[72:75], v77 offset:9216
	s_waitcnt lgkmcnt(1)
	v_mfma_f32_32x32x16_bf16 v[2:17], v[68:71], v[50:53], v[2:17]
	ds_read_b128 v[68:71], v67 offset:9248
	s_waitcnt lgkmcnt(1)
	v_mfma_f32_32x32x16_bf16 v[18:33], v[72:75], v[50:53], v[18:33]
	ds_read_b128 v[72:75], v77 offset:9248
	v_pk_fma_f32 v[34:35], v[34:35], v[76:77], v[66:67] op_sel_hi:[1,0,0]
	v_pk_fma_f32 v[36:37], v[36:37], v[76:77], v[66:67] op_sel_hi:[1,0,0]
	v_exp_f32_e32 v34, v34
	v_pk_add_f32 v[56:57], v[56:57], v[60:61]
	v_exp_f32_e32 v35, v35
	v_pk_add_f32 v[56:57], v[56:57], v[62:63]
	v_exp_f32_e32 v36, v36
	v_pk_fma_f32 v[38:39], v[38:39], v[76:77], v[66:67] op_sel_hi:[1,0,0]
	v_exp_f32_e32 v37, v37
	v_pk_add_f32 v[56:57], v[56:57], v[64:65]
	v_exp_f32_e32 v38, v38
	v_pk_fma_f32 v[40:41], v[40:41], v[76:77], v[66:67] op_sel_hi:[1,0,0]
	v_exp_f32_e32 v39, v39
	v_cvt_pk_bf16_f32 v58, v58, v59
	v_exp_f32_e32 v40, v40
	v_cvt_pk_bf16_f32 v59, v60, v61
	v_exp_f32_e32 v41, v41
	v_cvt_pk_bf16_f32 v60, v62, v63
	v_cvt_pk_bf16_f32 v61, v64, v65
	s_waitcnt lgkmcnt(1)
	s_nop 0
	v_mfma_f32_32x32x16_bf16 v[2:17], v[68:71], v[58:61], v[2:17]
	ds_read_b128 v[68:71], v67 offset:9280
	s_waitcnt lgkmcnt(1)
	v_mfma_f32_32x32x16_bf16 v[18:33], v[72:75], v[58:61], v[18:33]
	ds_read_b128 v[72:75], v77 offset:9280
	v_pk_fma_f32 v[42:43], v[42:43], v[76:77], v[66:67] op_sel_hi:[1,0,0]
	v_pk_fma_f32 v[44:45], v[44:45], v[76:77], v[66:67] op_sel_hi:[1,0,0]
	v_exp_f32_e32 v42, v42
	v_pk_add_f32 v[56:57], v[56:57], v[34:35]
	v_exp_f32_e32 v43, v43
	v_pk_add_f32 v[56:57], v[56:57], v[36:37]
	v_exp_f32_e32 v44, v44
	v_pk_fma_f32 v[46:47], v[46:47], v[76:77], v[66:67] op_sel_hi:[1,0,0]
	v_exp_f32_e32 v45, v45
	v_pk_add_f32 v[56:57], v[56:57], v[38:39]
	v_exp_f32_e32 v46, v46
	v_pk_fma_f32 v[48:49], v[48:49], v[76:77], v[66:67] op_sel_hi:[1,0,0]
	v_exp_f32_e32 v47, v47
	v_pk_add_f32 v[56:57], v[56:57], v[40:41]
	v_exp_f32_e32 v48, v48
	v_cvt_pk_bf16_f32 v34, v34, v35
	v_exp_f32_e32 v49, v49
	v_cvt_pk_bf16_f32 v35, v36, v37
	v_cvt_pk_bf16_f32 v36, v38, v39
	v_cvt_pk_bf16_f32 v37, v40, v41
	s_waitcnt lgkmcnt(1)
	s_nop 0
	v_mfma_f32_32x32x16_bf16 v[2:17], v[68:71], v[34:37], v[2:17]
	ds_read_b128 v[68:71], v67 offset:9312
	s_waitcnt lgkmcnt(1)
	v_mfma_f32_32x32x16_bf16 v[18:33], v[72:75], v[34:37], v[18:33]
	ds_read_b128 v[72:75], v77 offset:9312
	v_pk_add_f32 v[56:57], v[56:57], v[42:43]
	v_pk_add_f32 v[56:57], v[56:57], v[44:45]
	v_pk_add_f32 v[56:57], v[56:57], v[46:47]
	v_pk_add_f32 v[56:57], v[56:57], v[48:49]
	v_cvt_pk_bf16_f32 v42, v42, v43
	v_cvt_pk_bf16_f32 v43, v44, v45
	v_cvt_pk_bf16_f32 v44, v46, v47
	v_cvt_pk_bf16_f32 v45, v48, v49
	v_add_f32_e32 v56, v56, v57
	s_waitcnt lgkmcnt(1)
	v_mfma_f32_32x32x16_bf16 v[2:17], v[68:71], v[42:45], v[2:17]
	v_add_f32_e32 v151, v151, v56
	s_waitcnt lgkmcnt(0)
	v_mfma_f32_32x32x16_bf16 v[18:33], v[72:75], v[42:45], v[18:33]
